# baseline (speedup 1.0000x reference)
; __device__ __forceinline__ int ptid() { int t = __builtin_amdgcn_workitem_id_x(); asm volatile("" : "+v"(t)); return t; }
; #define RUNP(k) { run_phase<k>(p, smem); if (DBL_PHASE == k || ((DBL_MASK >> k) & 1)) { xcd_barrier(xb); run_phase<k>(p, smem); } }
; static __device__ __forceinline__ void phase4(const Params& p) {
;   const int wave = ptid() >> 6, lane = ptid() & 63;
;   const u16* Of = (const u16*)(p.out + DO_OF); const u16* Ob = (const u16*)(p.out + DO_OB);
;   const u16* Hp = (const u16*)(p.ws + WS_HP); u16* Hg = (u16*)(p.out + DO_OF);
;   for (int row = blockIdx.x * 4 + wave; row < T; row += gridDim.x * 4) {
;     const u32x4 a = *(const u32x4*)(Of + (size_t)row * 512 + lane * 8);
;     const u32x4 b = *(const u32x4*)(Ob + (size_t)row * 512 + lane * 8);
;     const u32x4 g = *(const u32x4*)(Hp + (size_t)row * 2560 + 2048 + lane * 8);
;     float o[8]; float ss = 0.f;
; __global__ void __launch_bounds__(256, 2) mega(Params p) {
;     ...
;   RUNP(4);
;   RUNP(5); xcd_barrier(xb);
.LBB0_423:
	s_or_b64 exec, exec, s[0:1]
	v_mov_b32_e32 v0, v174
	s_barrier
	v_readlane_b32 s98, v224, 0
	s_nop 3
	s_bitcmp1_b32 s98, 0
	s_cselect_b32 s99, 1, 0
	s_cbranch_scc1 .LBB0_426
.Lp4_body:
	v_mov_b32_e32 v0, v174
	v_readlane_b32 s0, v224, 8
	v_ashrrev_i32_e32 v1, 6, v0
	v_mov_b32_e32 v0, v174
	v_add_u32_e32 v4, s0, v1
	s_mov_b32 s0, 0x18000
	v_cmp_gt_i32_e32 vcc, s0, v4
	s_and_saveexec_b64 s[8:9], vcc
	s_cbranch_execz .LBB0_426
	v_lshlrev_b32_e32 v0, 3, v0
	v_and_b32_e32 v0, 0x1f8, v0
	v_mov_b32_e32 v7, 0
	v_lshlrev_b32_e32 v6, 1, v0
	v_lshl_add_u64 v[8:9], s[58:59], 0, v[6:7]
	s_mov_b64 s[0:1], 0x6000000
	v_lshl_add_u64 v[10:11], v[8:9], 0, s[0:1]
	s_lshl_b32 s2, s62, 2
	s_mov_b64 s[10:11], 0
	s_movk_i32 s3, 0x1400
	v_mov_b64_e32 v[12:13], s[60:61]
	v_lshlrev_b32_e32 v6, 1, v0
	s_movk_i32 s12, 0x1000
	v_mov_b32_e32 v16, 0x358637bd
	s_mov_b32 s13, 0x800000
	s_mov_b32 s20, 0x17fff

; #define TILE_LOOP(NT) for (int li_ = blockIdx.x >> 3, mtile, ntile; tile_map(li_, NT, mtile, ntile); li_ += gridDim.x >> 3)
; static __device__ __forceinline__ void phase_g1b(const Params& p, u16* sm) {
;   const u16* xn = (const u16*)(p.out + DO_XN);
;   const u16* Wt = (const u16*)(p.ws + WS_WIN) + (size_t)3232 * 1024;
;   u16* Gp = (u16*)(p.ws + WS_GP);
;   EPI_IDX
;   bool pre = false;
;   TILE_LOOP(16) {
;     const int m0 = mtile * 128, n0 = ntile * 128;
;     int mt2, nt2; const bool has_next = tile_map(li_ + (gridDim.x >> 3), 16, mt2, nt2);
;     f32x4 acc[4][4]; zero_acc(acc);
;     gemm_main(xn + (size_t)m0 * 1024, 1024, Wt + (size_t)n0 * 1024, 1024, 1024, acc, sm, pre,
;               has_next ? xn + (size_t)mt2 * 128 * 1024 : nullptr, has_next ? Wt + (size_t)nt2 * 128 * 1024 : nullptr);
.LBB0_426:
	s_or_b64 exec, exec, s[8:9]
	s_cmp_eq_u32 s99, 2
	s_cbranch_scc1 .Lp5_done
	v_readlane_b32 s0, v224, 0
	s_cmpk_lt_u32 s0, 0x3000
	v_mov_b32_e32 v0, v174
	s_cselect_b64 s[8:9], -1, 0
	s_cmpk_gt_u32 s0, 0x2fff
	s_cbranch_scc1 .LBB0_447
	s_add_u32 s33, s60, 0x3c650000
	v_and_b32_e32 v1, 15, v0
	v_and_b32_e32 v2, 64, v0
	v_ashrrev_i32_e32 v3, 1, v0
	s_movk_i32 s0, 0xffc0
	v_lshrrev_b32_e32 v0, 2, v0
	s_addc_u32 s42, s61, 0
	v_and_or_b32 v80, v3, s0, v1
	v_and_or_b32 v81, v0, 12, v2
	s_mov_b64 s[20:21], 0
	s_waitcnt vmcnt(29)
	v_mov_b32_e32 v65, 0
	s_mov_b64 s[0:1], 0x10000
	s_mov_b64 s[4:5], 0x20000
	s_mov_b64 s[6:7], 0x30000
	s_mov_b64 s[10:11], 0x80
	s_mov_b64 s[30:31], 0x10080
	s_mov_b64 s[34:35], 0x20080
	s_mov_b64 s[40:41], 0x30080
	s_mov_b64 s[44:45], 0x100
	s_mov_b64 s[46:47], 0x10100
	s_mov_b32 s43, s91
	s_waitcnt vmcnt(0)
	s_branch .LBB0_429

; #define RUNP(k) { run_phase<k>(p, smem); if (DBL_PHASE == k || ((DBL_MASK >> k) & 1)) { xcd_barrier(xb); run_phase<k>(p, smem); } }
; __global__ void __launch_bounds__(256, 2) mega(Params p) {
;     ...
;   RUNP(4);
;   RUNP(5); xcd_barrier(xb);
.LBB0_447:
	s_cmp_eq_u32 s99, 1
	s_cbranch_scc0 .Lp5_done
	s_mov_b32 s99, 2
	s_branch .Lp4_body
